# v30 + latency trims: step-0 early K3/V1 requests, attention gate-load prefetch, final-norm residual/gain prefetch
# baseline (speedup 1.0000x reference)
.LBB0_830:
	v_lshlrev_b32_e32 v0, 1, v204
	v_lshrrev_b32_e32 v2, 2, v204
	v_and_b32_e32 v209, 32, v0
	v_lshlrev_b32_e32 v211, 3, v204
	v_and_or_b32 v2, v2, 3, v212
	v_add_u32_e32 v0, 0, v209
	v_and_b32_e32 v210, 24, v211
	v_lshlrev_b32_e32 v208, 6, v2
	v_add3_u32 v217, v0, v210, v208
	v_max3_f32 v0, v48, v49, v32
	v_max3_f32 v2, v50, v51, v33
	s_add_i32 s6, s83, s93
	v_max3_f32 v0, v0, v34, v35
	v_max3_f32 v2, v2, v54, v55
	s_add_i32 s1, s13, 0x100
	v_max3_f32 v0, v0, v52, v53
	v_max3_f32 v2, v2, v38, v39
	s_lshr_b32 s1, s1, 6
	v_max3_f32 v0, v0, v36, v37
	v_max3_f32 v2, v2, v58, v59
	v_lshl_add_u32 v207, v212, 2, s87
	v_max3_f32 v0, v0, v56, v57
	v_max3_f32 v2, v2, v42, v43
	s_mov_b32 s10, 1
	v_max3_f32 v0, v0, v40, v41
	v_max3_f32 v2, v2, v62, v63
	s_mov_b32 s23, 0
	v_max3_f32 v0, v0, v60, v61
	v_max3_f32 v2, v2, v46, v47
	s_andn2_b64 vcc, exec, s[4:5]
	v_max3_f32 v0, v0, v44, v45
	v_cmp_gt_u32_e64 s[4:5], 32, v204
	v_max_f32_e32 v0, v0, v2
	s_nop 0
	v_mov_b32_e32 v2, v0
	s_nop 1
	v_permlane32_swap_b32_e32 v0, v2
	v_max_f32_e32 v0, v0, v2
	s_nop 0
	v_add_f32_e32 v215, v1, v0
	v_sub_f32_e32 v2, v48, v0
	v_sub_f32_e32 v3, v32, v0
	v_sub_f32_e32 v4, v49, v0
	v_sub_f32_e32 v5, v33, v0
	v_sub_f32_e32 v6, v50, v0
	s_nop 0
	v_xor_b32_e32 v64, 0x80000000, v215
	v_mov_b32_e32 v65, v64
	v_mov_b32_e32 v66, v64
	v_mov_b32_e32 v67, v64
	v_mov_b32_e32 v68, v64
	v_mov_b32_e32 v69, v64
	v_mov_b32_e32 v70, v64
	v_mov_b32_e32 v71, v64
	v_mov_b32_e32 v72, v64
	v_mov_b32_e32 v73, v64
	v_mov_b32_e32 v74, v64
	v_mov_b32_e32 v75, v64
	v_mov_b32_e32 v76, v64
	v_mov_b32_e32 v77, v64
	v_mov_b32_e32 v78, v64
	v_mov_b32_e32 v79, v64
	s_waitcnt vmcnt(3) lgkmcnt(0)
	s_barrier
	ds_read_b128 v[196:199], v214 offset:12288
	ds_read_b128 v[184:187], v214 offset:12800
	ds_read_b128 v[188:191], v214 offset:14336
	ds_read_b128 v[192:195], v214 offset:14848
	v_sub_f32_e32 v7, v34, v0
	v_sub_f32_e32 v8, v51, v0
	v_sub_f32_e32 v9, v35, v0
	v_sub_f32_e32 v10, v52, v0
	v_sub_f32_e32 v11, v36, v0
	v_sub_f32_e32 v12, v53, v0
	v_sub_f32_e32 v13, v37, v0
	v_sub_f32_e32 v14, v54, v0
	v_sub_f32_e32 v15, v38, v0
	v_sub_f32_e32 v32, v55, v0
	v_sub_f32_e32 v33, v39, v0
	v_sub_f32_e32 v34, v56, v0
	v_sub_f32_e32 v35, v40, v0
	v_sub_f32_e32 v36, v57, v0
	v_sub_f32_e32 v37, v41, v0
	v_sub_f32_e32 v38, v58, v0
	v_sub_f32_e32 v39, v42, v0
	v_sub_f32_e32 v40, v59, v0
	v_sub_f32_e32 v41, v43, v0
	v_sub_f32_e32 v42, v60, v0
	v_sub_f32_e32 v43, v44, v0
	v_sub_f32_e32 v44, v61, v0
	v_sub_f32_e32 v45, v45, v0
	v_sub_f32_e32 v48, v62, v0
	v_sub_f32_e32 v46, v46, v0
	v_sub_f32_e32 v49, v63, v0
	v_sub_f32_e32 v0, v47, v0
	v_exp_f32_e32 v96, v2
	v_exp_f32_e32 v97, v4
	v_exp_f32_e32 v98, v6
	v_exp_f32_e32 v99, v8
	v_exp_f32_e32 v100, v10
	v_exp_f32_e32 v101, v12
	v_exp_f32_e32 v102, v14
	v_exp_f32_e32 v103, v32
	v_exp_f32_e32 v104, v34
	v_exp_f32_e32 v105, v36
	v_exp_f32_e32 v106, v38
	v_exp_f32_e32 v107, v40
	v_exp_f32_e32 v108, v42
	v_exp_f32_e32 v109, v44
	v_exp_f32_e32 v110, v48
	v_exp_f32_e32 v111, v49
	v_exp_f32_e32 v80, v3
	v_exp_f32_e32 v81, v5
	v_exp_f32_e32 v82, v7
	v_exp_f32_e32 v83, v9
	v_exp_f32_e32 v84, v11
	v_exp_f32_e32 v85, v13
	v_exp_f32_e32 v86, v15
	v_exp_f32_e32 v87, v33
	v_exp_f32_e32 v88, v35
	v_exp_f32_e32 v89, v37
	v_exp_f32_e32 v90, v39
	v_exp_f32_e32 v91, v41
	v_exp_f32_e32 v92, v43
	v_exp_f32_e32 v93, v45
	v_exp_f32_e32 v94, v46
	v_exp_f32_e32 v95, v0
	s_cbranch_vccnz .LBB0_846
	v_mov_b32_e32 v14, v1
	v_mov_b32_e32 v15, v1
	v_mov_b32_e32 v0, v1
	v_mov_b32_e32 v2, v1
	v_mov_b32_e32 v3, v1
	v_mov_b32_e32 v4, v1
	v_mov_b32_e32 v5, v1
	v_mov_b32_e32 v6, v1
	v_mov_b32_e32 v7, v1
	v_mov_b32_e32 v8, v1
	v_mov_b32_e32 v9, v1
	v_mov_b32_e32 v10, v1
	v_mov_b32_e32 v11, v1
	v_mov_b32_e32 v12, v1
	v_mov_b32_e32 v13, v1
	v_mov_b64_e32 v[62:63], v[14:15]
	v_mov_b64_e32 v[46:47], v[14:15]
	s_add_i32 s66, s1, -5
	v_lshl_add_u32 v219, v205, 2, s87
	s_mov_b32 s62, 0
	s_mov_b32 s101, 0
	s_movk_i32 s23, 0x4000
	s_movk_i32 s10, 0x2000
	v_mov_b32_e32 v218, 0
	s_mov_b32 s67, 4
	s_mov_b64 s[6:7], s[52:53]
	s_mov_b64 s[58:59], s[50:51]
	s_mov_b64 s[60:61], s[48:49]
	v_mov_b64_e32 v[60:61], v[12:13]
	v_mov_b64_e32 v[58:59], v[10:11]
	v_mov_b64_e32 v[56:57], v[8:9]
	v_mov_b64_e32 v[54:55], v[6:7]
	v_mov_b64_e32 v[52:53], v[4:5]
	v_mov_b64_e32 v[50:51], v[2:3]
	v_mov_b64_e32 v[48:49], v[0:1]
	v_mov_b64_e32 v[44:45], v[12:13]
	v_mov_b64_e32 v[42:43], v[10:11]
	v_mov_b64_e32 v[40:41], v[8:9]
	v_mov_b64_e32 v[38:39], v[6:7]
	v_mov_b64_e32 v[36:37], v[4:5]
	v_mov_b64_e32 v[34:35], v[2:3]
	v_mov_b64_e32 v[32:33], v[0:1]
